# ctx w_in K loop (norm1 phase critical path) also merged into 4 phases; all GEMM K loops except the latent w_in loop are merged
# speedup vs baseline: 1.0005x; 1.0005x over previous
; #define PG8_STAGE(bufoff, gbase, voff) do { _Pragma("unroll") for (int _i = 0; _i < 2; ++_i) \
;     __builtin_amdgcn_global_load_lds((const unsigned*)((const char*)(gbase) + (voff)[_i]), (LAS unsigned*)(lds + (bufoff) + ldsw + _i * 8192), 16, 0, 0); } while (0)
; #define PG8_LDA(dst, b, h) do { _Pragma("unroll") for (int m = 0; m < 4; ++m) _Pragma("unroll") for (int k = 0; k < 2; ++k) dst[m][k] = *(const LAS bf16x8*)(lds + PG8_SA(b, h) + aoff + m * 2048 + k * 1024); } while (0)
; #define PG8_LDB(dst, b, h) do { _Pragma("unroll") for (int n = 0; n < 2; ++n) _Pragma("unroll") for (int k = 0; k < 2; ++k) dst[n][k] = *(const LAS bf16x8*)(lds + PG8_SB(b, h) + boff + n * 2048 + k * 1024); } while (0)
; #define PG8_MMA(ai, bj, At, Bt) do { __builtin_amdgcn_s_setprio(1); _Pragma("unroll") for (int m = 0; m < 4; ++m) _Pragma("unroll") for (int n = 0; n < 2; ++n) _Pragma("unroll") for (int k = 0; k < 2; ++k) \
;     acc[ai][bj][m][n] = __builtin_amdgcn_mfma_f32_16x16x32_bf16(Bt[n][k], At[m][k], acc[ai][bj][m][n], 0, 0, 0); __builtin_amdgcn_s_setprio(0); } while (0)
; #define PG8_WAIT_V(n) asm volatile("s_waitcnt vmcnt(" #n ")" ::: "memory")
; #define PG8_WAIT_L(n) asm volatile("s_waitcnt lgkmcnt(" #n ")" ::: "memory")
; #define PG8_BAR __builtin_amdgcn_s_barrier()
; #define PG8_SCHED __builtin_amdgcn_sched_barrier(0)
; template <class Epi, class Sched>
; DI void gemm_phase(LAS unsigned char* lds, const Gemm g, const Sched& S, const Epi& E) {
;     ...
;       PG8_LDB(B0, 0, 0); PG8_SCHED; PG8_LDA(At, 0, 0); PG8_STAGE(PG8_SA(1, 1), a1 + hstep, voffA);
;       PG8_WAIT_L(8); PG8_BAR; PG8_WAIT_L(0); PG8_MMA(0, 0, At, B0); PG8_BAR; PG8_SCHED;
;       PG8_LDB(B1, 0, 1); PG8_STAGE(PG8_SB(0, 0), b2, voffB);
;       PG8_BAR; PG8_WAIT_L(0); PG8_MMA(0, 1, At, B1); PG8_BAR;
;       PG8_LDA(At, 0, 1); PG8_STAGE(PG8_SA(0, 0), a2, voffA);
;       PG8_BAR; PG8_WAIT_L(0); PG8_MMA(1, 0, At, B0); PG8_BAR; PG8_SCHED;
;       PG8_STAGE(PG8_SB(0, 1), b2 + hstepB, voffB);
;       PG8_WAIT_V(6); PG8_BAR; PG8_MMA(1, 1, At, B1); PG8_BAR;
.LBB0_831:
	s_add_i32 s26, s10, 2
	s_add_u32 s11, s8, 0xfe000080
	s_addc_u32 s12, s9, -1
	s_cmp_lg_u32 s25, s10
	s_cselect_b32 s13, s12, 0
	s_cselect_b32 s12, s11, 0
	s_add_u32 s10, s6, s12
	s_addc_u32 s11, s7, s13
	s_add_i32 s27, 16, 0x10000
	v_add_u32_e32 v146, s27, v92
	ds_read_b128 v[94:97], v146
	ds_read_b128 v[152:155], v146 offset:1024
	ds_read_b128 v[156:159], v146 offset:2048
	ds_read_b128 v[160:163], v146 offset:3072
	s_add_u32 s12, s4, s12
	s_addc_u32 s13, s5, s13
	v_lshl_add_u64 v[146:147], v[88:89], 0, s[8:9]
	s_add_i32 m0, s18, 0xc000
	ds_read_b128 v[164:167], v93
	ds_read_b128 v[168:171], v93 offset:1024
	ds_read_b128 v[172:175], v93 offset:2048
	ds_read_b128 v[186:189], v93 offset:3072
	ds_read_b128 v[190:193], v93 offset:4096
	ds_read_b128 v[198:201], v93 offset:5120
	ds_read_b128 v[202:205], v93 offset:6144
	ds_read_b128 v[206:209], v93 offset:7168
	global_load_lds_dwordx4 v[146:147], off
	v_lshl_add_u64 v[146:147], v[90:91], 0, s[8:9]
	s_add_i32 m0, s18, 0xe000
	s_nop 0
	global_load_lds_dwordx4 v[146:147], off
	s_add_i32 s28, 16, 0x14000
	v_add_u32_e32 v146, s28, v92
	s_add_i32 s27, s27, s17
	ds_read_b128 v[214:217], v146
	ds_read_b128 v[218:221], v146 offset:1024
	ds_read_b128 v[222:225], v146 offset:2048
	ds_read_b128 v[226:229], v146 offset:3072
	s_waitcnt lgkmcnt(0)
	s_barrier
	v_mfma_f32_16x16x32_bf16 v[142:145], v[94:97], v[164:167], v[142:145]
	v_mfma_f32_16x16x32_bf16 v[138:141], v[156:159], v[164:167], v[138:141]
	v_mfma_f32_16x16x32_bf16 v[126:129], v[94:97], v[172:175], v[126:129]
	v_mfma_f32_16x16x32_bf16 v[122:125], v[156:159], v[172:175], v[122:125]
	v_mfma_f32_16x16x32_bf16 v[110:113], v[94:97], v[190:193], v[110:113]
	v_mfma_f32_16x16x32_bf16 v[106:109], v[156:159], v[190:193], v[106:109]
	v_mfma_f32_16x16x32_bf16 v[78:81], v[94:97], v[202:205], v[78:81]
	v_mfma_f32_16x16x32_bf16 v[74:77], v[156:159], v[202:205], v[74:77]
	v_mfma_f32_16x16x32_bf16 v[142:145], v[152:155], v[168:171], v[142:145]
	v_mfma_f32_16x16x32_bf16 v[138:141], v[160:163], v[168:171], v[138:141]
	v_mfma_f32_16x16x32_bf16 v[126:129], v[152:155], v[186:189], v[126:129]
	v_mfma_f32_16x16x32_bf16 v[122:125], v[160:163], v[186:189], v[122:125]
	v_mfma_f32_16x16x32_bf16 v[110:113], v[152:155], v[198:201], v[110:113]
	v_mfma_f32_16x16x32_bf16 v[106:109], v[160:163], v[198:201], v[106:109]
	v_mfma_f32_16x16x32_bf16 v[78:81], v[152:155], v[206:209], v[78:81]
	v_mfma_f32_16x16x32_bf16 v[74:77], v[160:163], v[206:209], v[74:77]
	v_mfma_f32_16x16x32_bf16 v[134:137], v[214:217], v[164:167], v[134:137]
	v_mfma_f32_16x16x32_bf16 v[130:133], v[222:225], v[164:167], v[130:133]
	v_mfma_f32_16x16x32_bf16 v[118:121], v[214:217], v[172:175], v[118:121]
	v_mfma_f32_16x16x32_bf16 v[114:117], v[222:225], v[172:175], v[114:117]
	v_mfma_f32_16x16x32_bf16 v[102:105], v[214:217], v[190:193], v[102:105]
	v_mfma_f32_16x16x32_bf16 v[98:101], v[222:225], v[190:193], v[98:101]
	v_mfma_f32_16x16x32_bf16 v[70:73], v[214:217], v[202:205], v[70:73]
	v_mfma_f32_16x16x32_bf16 v[66:69], v[222:225], v[202:205], v[66:69]
	v_mfma_f32_16x16x32_bf16 v[134:137], v[218:221], v[168:171], v[134:137]
	v_mfma_f32_16x16x32_bf16 v[130:133], v[226:229], v[168:171], v[130:133]
	v_mfma_f32_16x16x32_bf16 v[118:121], v[218:221], v[186:189], v[118:121]
	v_mfma_f32_16x16x32_bf16 v[114:117], v[226:229], v[186:189], v[114:117]
	v_mfma_f32_16x16x32_bf16 v[102:105], v[218:221], v[198:201], v[102:105]
	v_mfma_f32_16x16x32_bf16 v[98:101], v[226:229], v[198:201], v[98:101]
	v_mfma_f32_16x16x32_bf16 v[70:73], v[218:221], v[206:209], v[70:73]
	v_mfma_f32_16x16x32_bf16 v[66:69], v[226:229], v[206:209], v[66:69]
	s_mov_b32 m0, s18
	v_lshl_add_u64 v[230:231], s[10:11], 0, v[86:87]
	s_barrier
	ds_read_b128 v[164:167], v93 offset:16384
	ds_read_b128 v[168:171], v93 offset:17408
	ds_read_b128 v[172:175], v93 offset:18432
	ds_read_b128 v[186:189], v93 offset:19456
	ds_read_b128 v[190:193], v93 offset:20480
	ds_read_b128 v[198:201], v93 offset:21504
	ds_read_b128 v[202:205], v93 offset:22528
	ds_read_b128 v[206:209], v93 offset:23552
	global_load_lds_dwordx4 v[230:231], off
	v_lshl_add_u64 v[232:233], s[10:11], 0, v[84:85]
	s_mov_b32 m0, s19
	s_nop 0
	global_load_lds_dwordx4 v[232:233], off
	v_lshl_add_u64 v[238:239], s[12:13], 0, v[0:1]
	s_mov_b32 m0, s27
	v_lshl_add_u64 v[176:177], s[12:13], 0, v[82:83]
	global_load_lds_dwordx4 v[238:239], off
	s_add_i32 m0, s27, 0x2000
	s_nop 0
	global_load_lds_dwordx4 v[176:177], off
	s_add_u32 s12, s12, s2
	s_addc_u32 s13, s13, s3
	s_add_i32 s27, s28, s17
	v_lshl_add_u64 v[234:235], s[12:13], 0, v[0:1]
	s_mov_b32 m0, s27
	v_lshl_add_u64 v[236:237], s[12:13], 0, v[82:83]
	global_load_lds_dwordx4 v[234:235], off
	s_add_i32 m0, s27, 0x2000
	s_nop 0
	global_load_lds_dwordx4 v[236:237], off
	s_waitcnt vmcnt(6)
	s_waitcnt lgkmcnt(0)
	s_barrier
; #define PG8_STAGE(bufoff, gbase, voff) do { _Pragma("unroll") for (int _i = 0; _i < 2; ++_i) \
;     __builtin_amdgcn_global_load_lds((const unsigned*)((const char*)(gbase) + (voff)[_i]), (LAS unsigned*)(lds + (bufoff) + ldsw + _i * 8192), 16, 0, 0); } while (0)
; #define PG8_LDA(dst, b, h) do { _Pragma("unroll") for (int m = 0; m < 4; ++m) _Pragma("unroll") for (int k = 0; k < 2; ++k) dst[m][k] = *(const LAS bf16x8*)(lds + PG8_SA(b, h) + aoff + m * 2048 + k * 1024); } while (0)
; #define PG8_LDB(dst, b, h) do { _Pragma("unroll") for (int n = 0; n < 2; ++n) _Pragma("unroll") for (int k = 0; k < 2; ++k) dst[n][k] = *(const LAS bf16x8*)(lds + PG8_SB(b, h) + boff + n * 2048 + k * 1024); } while (0)
; #define PG8_MMA(ai, bj, At, Bt) do { __builtin_amdgcn_s_setprio(1); _Pragma("unroll") for (int m = 0; m < 4; ++m) _Pragma("unroll") for (int n = 0; n < 2; ++n) _Pragma("unroll") for (int k = 0; k < 2; ++k) \
;     acc[ai][bj][m][n] = __builtin_amdgcn_mfma_f32_16x16x32_bf16(Bt[n][k], At[m][k], acc[ai][bj][m][n], 0, 0, 0); __builtin_amdgcn_s_setprio(0); } while (0)
; #define PG8_WAIT_V(n) asm volatile("s_waitcnt vmcnt(" #n ")" ::: "memory")
; #define PG8_WAIT_L(n) asm volatile("s_waitcnt lgkmcnt(" #n ")" ::: "memory")
; #define PG8_BAR __builtin_amdgcn_s_barrier()
; #define PG8_SCHED __builtin_amdgcn_sched_barrier(0)
; template <class Epi, class Sched>
; DI void gemm_phase(LAS unsigned char* lds, const Gemm g, const Sched& S, const Epi& E) {
;     ...
;       PG8_WAIT_V(6); PG8_BAR; PG8_MMA(1, 1, At, B1); PG8_BAR;
;       PG8_LDB(B0, 1, 0); PG8_SCHED; PG8_LDA(At, 1, 0); PG8_STAGE(PG8_SA(0, 1), a2 + hstep, voffA);
;       PG8_WAIT_L(8); PG8_BAR; PG8_WAIT_L(0); PG8_MMA(0, 0, At, B0); PG8_BAR; PG8_SCHED;
;       PG8_LDB(B1, 1, 1); PG8_STAGE(PG8_SB(1, 0), b3, voffB);
;       PG8_BAR; PG8_WAIT_L(0); PG8_MMA(0, 1, At, B1); PG8_BAR;
;       PG8_LDA(At, 1, 1); PG8_STAGE(PG8_SA(1, 0), a3, voffA);
;       PG8_BAR; PG8_WAIT_L(0); PG8_MMA(1, 0, At, B0); PG8_BAR; PG8_SCHED;
	v_mfma_f32_16x16x32_bf16 v[62:65], v[94:97], v[164:167], v[62:65]
	v_mfma_f32_16x16x32_bf16 v[58:61], v[156:159], v[164:167], v[58:61]
	v_mfma_f32_16x16x32_bf16 v[46:49], v[94:97], v[172:175], v[46:49]
	v_mfma_f32_16x16x32_bf16 v[42:45], v[156:159], v[172:175], v[42:45]
	v_mfma_f32_16x16x32_bf16 v[30:33], v[94:97], v[190:193], v[30:33]
	v_mfma_f32_16x16x32_bf16 v[26:29], v[156:159], v[190:193], v[26:29]
	v_mfma_f32_16x16x32_bf16 v[14:17], v[94:97], v[202:205], v[14:17]
	v_mfma_f32_16x16x32_bf16 v[10:13], v[156:159], v[202:205], v[10:13]
	v_mfma_f32_16x16x32_bf16 v[62:65], v[152:155], v[168:171], v[62:65]
	v_mfma_f32_16x16x32_bf16 v[58:61], v[160:163], v[168:171], v[58:61]
	v_mfma_f32_16x16x32_bf16 v[46:49], v[152:155], v[186:189], v[46:49]
	v_mfma_f32_16x16x32_bf16 v[42:45], v[160:163], v[186:189], v[42:45]
	v_mfma_f32_16x16x32_bf16 v[30:33], v[152:155], v[198:201], v[30:33]
	v_mfma_f32_16x16x32_bf16 v[26:29], v[160:163], v[198:201], v[26:29]
	v_mfma_f32_16x16x32_bf16 v[14:17], v[152:155], v[206:209], v[14:17]
	v_mfma_f32_16x16x32_bf16 v[10:13], v[160:163], v[206:209], v[10:13]
	v_mfma_f32_16x16x32_bf16 v[54:57], v[214:217], v[164:167], v[54:57]
	v_mfma_f32_16x16x32_bf16 v[50:53], v[222:225], v[164:167], v[50:53]
	v_mfma_f32_16x16x32_bf16 v[38:41], v[214:217], v[172:175], v[38:41]
	v_mfma_f32_16x16x32_bf16 v[34:37], v[222:225], v[172:175], v[34:37]
	v_mfma_f32_16x16x32_bf16 v[22:25], v[214:217], v[190:193], v[22:25]
	v_mfma_f32_16x16x32_bf16 v[18:21], v[222:225], v[190:193], v[18:21]
	v_mfma_f32_16x16x32_bf16 v[6:9], v[214:217], v[202:205], v[6:9]
	v_mfma_f32_16x16x32_bf16 v[2:5], v[222:225], v[202:205], v[2:5]
	v_mfma_f32_16x16x32_bf16 v[54:57], v[218:221], v[168:171], v[54:57]
	v_mfma_f32_16x16x32_bf16 v[50:53], v[226:229], v[168:171], v[50:53]
	v_mfma_f32_16x16x32_bf16 v[38:41], v[218:221], v[186:189], v[38:41]
	v_mfma_f32_16x16x32_bf16 v[34:37], v[226:229], v[186:189], v[34:37]
	v_mfma_f32_16x16x32_bf16 v[22:25], v[218:221], v[198:201], v[22:25]
	v_mfma_f32_16x16x32_bf16 v[18:21], v[226:229], v[198:201], v[18:21]
	v_mfma_f32_16x16x32_bf16 v[6:9], v[218:221], v[206:209], v[6:9]
	v_mfma_f32_16x16x32_bf16 v[2:5], v[226:229], v[206:209], v[2:5]
	s_add_i32 s12, 16, 0x18000
	v_add_u32_e32 v149, s12, v92
	s_barrier
	ds_read_b128 v[94:97], v149
	ds_read_b128 v[152:155], v149 offset:1024
	ds_read_b128 v[156:159], v149 offset:2048
	ds_read_b128 v[160:163], v149 offset:3072
	s_add_u32 s10, s10, s0
	s_addc_u32 s11, s11, s1
	s_mov_b32 m0, s20
	v_lshl_add_u64 v[214:215], s[10:11], 0, v[86:87]
	ds_read_b128 v[164:167], v93 offset:32768
	ds_read_b128 v[168:171], v93 offset:33792
	ds_read_b128 v[172:175], v93 offset:34816
	ds_read_b128 v[186:189], v93 offset:35840
	ds_read_b128 v[190:193], v93 offset:36864
	ds_read_b128 v[198:201], v93 offset:37888
	ds_read_b128 v[202:205], v93 offset:38912
	ds_read_b128 v[206:209], v93 offset:39936
	global_load_lds_dwordx4 v[214:215], off
	v_lshl_add_u64 v[214:215], s[10:11], 0, v[84:85]
	s_mov_b32 m0, s21
	s_nop 0
	global_load_lds_dwordx4 v[214:215], off
	s_add_i32 s10, 16, 0x1c000
	s_add_i32 s11, s12, s17
	v_add_u32_e32 v149, s10, v92
	ds_read_b128 v[214:217], v149
	ds_read_b128 v[218:221], v149 offset:1024
	ds_read_b128 v[222:225], v149 offset:2048
	ds_read_b128 v[226:229], v149 offset:3072
	s_waitcnt lgkmcnt(0)
	s_barrier
	v_mfma_f32_16x16x32_bf16 v[142:145], v[94:97], v[164:167], v[142:145]
	v_mfma_f32_16x16x32_bf16 v[138:141], v[156:159], v[164:167], v[138:141]
	v_mfma_f32_16x16x32_bf16 v[126:129], v[94:97], v[172:175], v[126:129]
	v_mfma_f32_16x16x32_bf16 v[122:125], v[156:159], v[172:175], v[122:125]
	v_mfma_f32_16x16x32_bf16 v[110:113], v[94:97], v[190:193], v[110:113]
	v_mfma_f32_16x16x32_bf16 v[106:109], v[156:159], v[190:193], v[106:109]
	v_mfma_f32_16x16x32_bf16 v[78:81], v[94:97], v[202:205], v[78:81]
	v_mfma_f32_16x16x32_bf16 v[74:77], v[156:159], v[202:205], v[74:77]
	v_mfma_f32_16x16x32_bf16 v[142:145], v[152:155], v[168:171], v[142:145]
	v_mfma_f32_16x16x32_bf16 v[138:141], v[160:163], v[168:171], v[138:141]
	v_mfma_f32_16x16x32_bf16 v[126:129], v[152:155], v[186:189], v[126:129]
	v_mfma_f32_16x16x32_bf16 v[122:125], v[160:163], v[186:189], v[122:125]
	v_mfma_f32_16x16x32_bf16 v[110:113], v[152:155], v[198:201], v[110:113]
	v_mfma_f32_16x16x32_bf16 v[106:109], v[160:163], v[198:201], v[106:109]
	v_mfma_f32_16x16x32_bf16 v[78:81], v[152:155], v[206:209], v[78:81]
	v_mfma_f32_16x16x32_bf16 v[74:77], v[160:163], v[206:209], v[74:77]
	v_mfma_f32_16x16x32_bf16 v[134:137], v[214:217], v[164:167], v[134:137]
	v_mfma_f32_16x16x32_bf16 v[130:133], v[222:225], v[164:167], v[130:133]
	v_mfma_f32_16x16x32_bf16 v[118:121], v[214:217], v[172:175], v[118:121]
	v_mfma_f32_16x16x32_bf16 v[114:117], v[222:225], v[172:175], v[114:117]
	v_mfma_f32_16x16x32_bf16 v[102:105], v[214:217], v[190:193], v[102:105]
	v_mfma_f32_16x16x32_bf16 v[98:101], v[222:225], v[190:193], v[98:101]
	v_mfma_f32_16x16x32_bf16 v[70:73], v[214:217], v[202:205], v[70:73]
	v_mfma_f32_16x16x32_bf16 v[66:69], v[222:225], v[202:205], v[66:69]
	v_mfma_f32_16x16x32_bf16 v[134:137], v[218:221], v[168:171], v[134:137]
	v_mfma_f32_16x16x32_bf16 v[130:133], v[226:229], v[168:171], v[130:133]
	v_mfma_f32_16x16x32_bf16 v[118:121], v[218:221], v[186:189], v[118:121]
	v_mfma_f32_16x16x32_bf16 v[114:117], v[226:229], v[186:189], v[114:117]
	v_mfma_f32_16x16x32_bf16 v[102:105], v[218:221], v[198:201], v[102:105]
	v_mfma_f32_16x16x32_bf16 v[98:101], v[226:229], v[198:201], v[98:101]
	v_mfma_f32_16x16x32_bf16 v[70:73], v[218:221], v[206:209], v[70:73]
	v_mfma_f32_16x16x32_bf16 v[66:69], v[226:229], v[206:209], v[66:69]
	s_mov_b32 m0, s22
	v_lshl_add_u64 v[146:147], v[230:231], 0, s[70:71]
	s_barrier
; #define PG8_STAGE(bufoff, gbase, voff) do { _Pragma("unroll") for (int _i = 0; _i < 2; ++_i) \
;     __builtin_amdgcn_global_load_lds((const unsigned*)((const char*)(gbase) + (voff)[_i]), (LAS unsigned*)(lds + (bufoff) + ldsw + _i * 8192), 16, 0, 0); } while (0)
; #define PG8_LDA(dst, b, h) do { _Pragma("unroll") for (int m = 0; m < 4; ++m) _Pragma("unroll") for (int k = 0; k < 2; ++k) dst[m][k] = *(const LAS bf16x8*)(lds + PG8_SA(b, h) + aoff + m * 2048 + k * 1024); } while (0)
; #define PG8_MMA(ai, bj, At, Bt) do { __builtin_amdgcn_s_setprio(1); _Pragma("unroll") for (int m = 0; m < 4; ++m) _Pragma("unroll") for (int n = 0; n < 2; ++n) _Pragma("unroll") for (int k = 0; k < 2; ++k) \
;     acc[ai][bj][m][n] = __builtin_amdgcn_mfma_f32_16x16x32_bf16(Bt[n][k], At[m][k], acc[ai][bj][m][n], 0, 0, 0); __builtin_amdgcn_s_setprio(0); } while (0)
; #define PG8_WAIT_V(n) asm volatile("s_waitcnt vmcnt(" #n ")" ::: "memory")
; #define PG8_WAIT_L(n) asm volatile("s_waitcnt lgkmcnt(" #n ")" ::: "memory")
; #define PG8_BAR __builtin_amdgcn_s_barrier()
; #define PG8_SCHED __builtin_amdgcn_sched_barrier(0)
; template <class Epi, class Sched>
; DI void gemm_phase(LAS unsigned char* lds, const Gemm g, const Sched& S, const Epi& E) {
;     ...
;       PG8_LDA(At, 1, 1); PG8_STAGE(PG8_SA(1, 0), a3, voffA);
;       PG8_BAR; PG8_WAIT_L(0); PG8_MMA(1, 0, At, B0); PG8_BAR; PG8_SCHED;
;       PG8_STAGE(PG8_SB(1, 1), b3 + hstepB, voffB);
;       PG8_WAIT_V(6); PG8_BAR; PG8_MMA(1, 1, At, B1); PG8_BAR;
;     }
	ds_read_b128 v[164:167], v93 offset:49152
	ds_read_b128 v[168:171], v93 offset:50176
	ds_read_b128 v[172:175], v93 offset:51200
	ds_read_b128 v[186:189], v93 offset:52224
	ds_read_b128 v[190:193], v93 offset:53248
	ds_read_b128 v[198:201], v93 offset:54272
	ds_read_b128 v[202:205], v93 offset:55296
	ds_read_b128 v[206:209], v93 offset:56320
	global_load_lds_dwordx4 v[146:147], off
	v_lshl_add_u64 v[146:147], v[232:233], 0, s[70:71]
	s_mov_b32 m0, s23
	s_nop 0
	global_load_lds_dwordx4 v[146:147], off
	v_lshl_add_u64 v[238:239], v[238:239], 0, s[70:71]
	s_mov_b32 m0, s11
	s_nop 0
	global_load_lds_dwordx4 v[238:239], off
	v_lshl_add_u64 v[146:147], v[176:177], 0, s[70:71]
	s_add_i32 m0, s11, 0x2000
	s_nop 0
	global_load_lds_dwordx4 v[146:147], off
	s_add_i32 s10, s10, s17
	v_lshl_add_u64 v[240:241], v[234:235], 0, s[70:71]
	s_mov_b32 m0, s10
	s_nop 0
	global_load_lds_dwordx4 v[240:241], off
	v_lshl_add_u64 v[240:241], v[236:237], 0, s[70:71]
	s_add_i32 m0, s10, 0x2000
	s_nop 0
	global_load_lds_dwordx4 v[240:241], off
	s_waitcnt vmcnt(6)
	s_waitcnt lgkmcnt(0)
	s_barrier
	v_mfma_f32_16x16x32_bf16 v[62:65], v[94:97], v[164:167], v[62:65]
	v_mfma_f32_16x16x32_bf16 v[58:61], v[156:159], v[164:167], v[58:61]
	v_mfma_f32_16x16x32_bf16 v[46:49], v[94:97], v[172:175], v[46:49]
	v_mfma_f32_16x16x32_bf16 v[42:45], v[156:159], v[172:175], v[42:45]
	v_mfma_f32_16x16x32_bf16 v[30:33], v[94:97], v[190:193], v[30:33]
	v_mfma_f32_16x16x32_bf16 v[26:29], v[156:159], v[190:193], v[26:29]
	v_mfma_f32_16x16x32_bf16 v[14:17], v[94:97], v[202:205], v[14:17]
	v_mfma_f32_16x16x32_bf16 v[10:13], v[156:159], v[202:205], v[10:13]
	v_mfma_f32_16x16x32_bf16 v[62:65], v[152:155], v[168:171], v[62:65]
	v_mfma_f32_16x16x32_bf16 v[58:61], v[160:163], v[168:171], v[58:61]
	v_mfma_f32_16x16x32_bf16 v[46:49], v[152:155], v[186:189], v[46:49]
	v_mfma_f32_16x16x32_bf16 v[42:45], v[160:163], v[186:189], v[42:45]
	v_mfma_f32_16x16x32_bf16 v[30:33], v[152:155], v[198:201], v[30:33]
	v_mfma_f32_16x16x32_bf16 v[26:29], v[160:163], v[198:201], v[26:29]
	v_mfma_f32_16x16x32_bf16 v[14:17], v[152:155], v[206:209], v[14:17]
	v_mfma_f32_16x16x32_bf16 v[10:13], v[160:163], v[206:209], v[10:13]
	v_mfma_f32_16x16x32_bf16 v[54:57], v[214:217], v[164:167], v[54:57]
	v_mfma_f32_16x16x32_bf16 v[50:53], v[222:225], v[164:167], v[50:53]
	v_mfma_f32_16x16x32_bf16 v[38:41], v[214:217], v[172:175], v[38:41]
	v_mfma_f32_16x16x32_bf16 v[34:37], v[222:225], v[172:175], v[34:37]
	v_mfma_f32_16x16x32_bf16 v[22:25], v[214:217], v[190:193], v[22:25]
	v_mfma_f32_16x16x32_bf16 v[18:21], v[222:225], v[190:193], v[18:21]
	v_mfma_f32_16x16x32_bf16 v[6:9], v[214:217], v[202:205], v[6:9]
	v_mfma_f32_16x16x32_bf16 v[2:5], v[222:225], v[202:205], v[2:5]
	v_mfma_f32_16x16x32_bf16 v[54:57], v[218:221], v[168:171], v[54:57]
	v_mfma_f32_16x16x32_bf16 v[50:53], v[226:229], v[168:171], v[50:53]
	v_mfma_f32_16x16x32_bf16 v[38:41], v[218:221], v[186:189], v[38:41]
	v_mfma_f32_16x16x32_bf16 v[34:37], v[226:229], v[186:189], v[34:37]
	v_mfma_f32_16x16x32_bf16 v[22:25], v[218:221], v[198:201], v[22:25]
	v_mfma_f32_16x16x32_bf16 v[18:21], v[226:229], v[198:201], v[18:21]
	v_mfma_f32_16x16x32_bf16 v[6:9], v[218:221], v[206:209], v[6:9]
	v_mfma_f32_16x16x32_bf16 v[2:5], v[226:229], v[206:209], v[2:5]
	s_add_u32 s8, s8, 0x100
	s_addc_u32 s9, s9, 0
	s_cmp_ge_i32 s26, s24
	s_mov_b32 s10, s26
	s_barrier
	s_cbranch_scc0 .LBB0_831
